# up phase: next-unit row-stats loads hoisted to mid-epilogue into free regs, counted wait vmcnt(4) at reduction
# speedup vs baseline: 1.0172x; 1.0019x over previous
.LBB0_940:
	s_waitcnt vmcnt(4) lgkmcnt(0)
	v_pk_add_f32 v[224:225], v[224:225], v[226:227]
	v_pk_add_f32 v[150:151], v[150:151], v[152:153]
	v_pk_add_f32 v[224:225], v[224:225], 0 op_sel_hi:[1,0]
	v_pk_add_f32 v[216:217], v[216:217], v[218:219]
	v_pk_add_f32 v[150:151], v[150:151], 0 op_sel_hi:[1,0]
	v_pk_add_f32 v[130:131], v[130:131], v[132:133]
	v_pk_add_f32 v[216:217], v[224:225], v[216:217]
	v_pk_add_f32 v[212:213], v[212:213], v[214:215]
	v_pk_add_f32 v[130:131], v[150:151], v[130:131]
	v_pk_add_f32 v[118:119], v[118:119], v[120:121]
	v_pk_add_f32 v[212:213], v[216:217], v[212:213]
	v_pk_add_f32 v[208:209], v[208:209], v[210:211]
	v_pk_add_f32 v[118:119], v[130:131], v[118:119]
	v_pk_add_f32 v[104:105], v[104:105], v[106:107]
	v_pk_add_f32 v[208:209], v[212:213], v[208:209]
	v_pk_add_f32 v[204:205], v[204:205], v[206:207]
	v_pk_add_f32 v[104:105], v[118:119], v[104:105]
	v_pk_add_f32 v[100:101], v[100:101], v[102:103]
	v_pk_add_f32 v[204:205], v[208:209], v[204:205]
	v_pk_add_f32 v[200:201], v[200:201], v[202:203]
	v_pk_add_f32 v[100:101], v[104:105], v[100:101]
	v_pk_add_f32 v[96:97], v[96:97], v[98:99]
	v_pk_add_f32 v[200:201], v[204:205], v[200:201]
	v_pk_add_f32 v[196:197], v[196:197], v[198:199]
	v_pk_add_f32 v[96:97], v[100:101], v[96:97]
	v_pk_add_f32 v[92:93], v[92:93], v[94:95]
	v_pk_add_f32 v[196:197], v[200:201], v[196:197]
	v_pk_add_f32 v[154:155], v[154:155], v[156:157]
	v_pk_add_f32 v[92:93], v[96:97], v[92:93]
	v_pk_add_f32 v[88:89], v[88:89], v[90:91]
	v_pk_add_f32 v[154:155], v[196:197], v[154:155]
	v_pk_add_f32 v[88:89], v[92:93], v[88:89]
	v_pk_mul_f32 v[176:177], v[154:155], s[64:65] op_sel_hi:[1,0]
	v_pk_mul_f32 v[174:175], v[88:89], s[64:65] op_sel_hi:[1,0]
	v_fma_f32 v154, -v176, v176, v177
	v_fma_f32 v88, -v174, v174, v175
	v_max_f32_e32 v154, 0, v154
	v_max_f32_e32 v88, 0, v88
	v_add_f32_e32 v154, 0x3727c5ac, v154
	v_add_f32_e32 v88, 0x3727c5ac, v88
	v_mul_f32_e32 v155, 0x4b800000, v154
	v_cmp_gt_f32_e32 vcc, s35, v154
	v_mul_f32_e32 v89, 0x4b800000, v88
	v_cmp_gt_f32_e64 s[0:1], s35, v88
	v_cndmask_b32_e32 v154, v154, v155, vcc
	v_rsq_f32_e32 v154, v154
	v_cndmask_b32_e64 v88, v88, v89, s[0:1]
	v_rsq_f32_e32 v88, v88
	v_mul_f32_e32 v89, 0x45800000, v154
	v_cndmask_b32_e32 v179, v154, v89, vcc
	v_mul_f32_e32 v90, 0x45800000, v88
	v_cndmask_b32_e64 v175, v88, v90, s[0:1]
	s_mov_b64 s[0:1], 0

.Lup_sig_skip:
	v_mbcnt_lo_u32_b32 v177, -1, 0
	v_mbcnt_hi_u32_b32 v177, -1, v177
	s_lshl_b32 s3, s3, 11
	v_and_b32_e32 v180, 15, v177
	v_ashrrev_i32_e32 v183, 4, v177
	s_add_i32 s3, s53, s3
	v_lshlrev_b32_e32 v181, 2, v180
	ds_bpermute_b32 v182, v181, v176
	ds_bpermute_b32 v184, v181, v179
	v_lshl_add_u32 v114, v183, 5, s3
	ds_read_b128 v[142:145], v114
	ds_read_b128 v[122:125], v114 offset:16
	ds_read_b128 v[146:149], v114 offset:1024
	ds_read_b128 v[126:129], v114 offset:1040
	ds_read_b128 v[138:141], v114 offset:512
	ds_read_b128 v[110:113], v114 offset:528
	ds_read_b128 v[134:137], v114 offset:1536
	ds_read_b128 v[114:117], v114 offset:1552
	s_lshl_b32 s23, s36, 7
	s_waitcnt lgkmcnt(0)
	v_pk_fma_f32 v[158:159], v[142:143], v[182:183], v[158:159] op_sel_hi:[1,0,1] neg_lo:[1,0,0] neg_hi:[1,0,0]
	v_pk_fma_f32 v[160:161], v[144:145], v[182:183], v[160:161] op_sel_hi:[1,0,1] neg_lo:[1,0,0] neg_hi:[1,0,0]
	v_pk_fma_f32 v[198:199], v[158:159], v[184:185], v[146:147] op_sel_hi:[1,0,1]
	s_or_b32 s23, s23, s49
	v_mul_f32_e32 v158, 0xbfb8aa3b, v198
	v_exp_f32_e32 v158, v158
	v_mul_f32_e32 v159, 0xbfb8aa3b, v199
	v_exp_f32_e32 v159, v159
	v_pk_fma_f32 v[160:161], v[160:161], v[184:185], v[148:149] op_sel_hi:[1,0,1]
	v_add_f32_e32 v158, 1.0, v158
	v_lshl_add_u32 v196, v183, 3, s23
	v_rcp_f32_e32 v200, v158
	v_add_f32_e32 v158, 1.0, v159
	v_pk_fma_f32 v[154:155], v[138:139], v[182:183], v[154:155] op_sel_hi:[1,0,1] neg_lo:[1,0,0] neg_hi:[1,0,0]
	v_mul_f32_e32 v183, 0xbfb8aa3b, v160
	v_rcp_f32_e32 v201, v158
	v_pk_fma_f32 v[154:155], v[154:155], v[184:185], v[134:135] op_sel_hi:[1,0,1]
	v_exp_f32_e32 v183, v183
	v_mul_f32_e32 v185, 0xbfb8aa3b, v161
	v_exp_f32_e32 v185, v185
	v_ashrrev_i32_e32 v197, 31, v196
	v_lshl_add_u64 v[158:159], v[196:197], 1, s[92:93]
	v_pk_mul_f32 v[196:197], v[198:199], v[200:201]
	v_add_f32_e32 v183, 1.0, v183
	v_pk_mul_f32 v[154:155], v[154:155], v[196:197]
	v_rcp_f32_e32 v196, v183
	v_pk_fma_f32 v[156:157], v[140:141], v[182:183], v[156:157] op_sel_hi:[1,0,1] neg_lo:[1,0,0] neg_hi:[1,0,0]
	v_add_f32_e32 v183, 1.0, v185
	v_rcp_f32_e32 v197, v183
	v_pk_fma_f32 v[150:151], v[122:123], v[182:183], v[150:151] op_sel_hi:[1,0,1] neg_lo:[1,0,0] neg_hi:[1,0,0]
	v_pk_fma_f32 v[156:157], v[156:157], v[184:185], v[136:137] op_sel_hi:[1,0,1]
	v_pk_fma_f32 v[150:151], v[150:151], v[184:185], v[126:127] op_sel_hi:[1,0,1]
	v_pk_mul_f32 v[160:161], v[160:161], v[196:197]
	v_mul_f32_e32 v183, 0xbfb8aa3b, v150
	v_exp_f32_e32 v183, v183
	v_pk_mul_f32 v[156:157], v[156:157], v[160:161]
	v_mul_f32_e32 v161, 0xbfb8aa3b, v151
	v_exp_f32_e32 v161, v161
	v_pk_fma_f32 v[152:153], v[124:125], v[182:183], v[152:153] op_sel_hi:[1,0,1] neg_lo:[1,0,0] neg_hi:[1,0,0]
	v_pk_fma_f32 v[130:131], v[110:111], v[182:183], v[130:131] op_sel_hi:[1,0,1] neg_lo:[1,0,0] neg_hi:[1,0,0]
	v_pk_fma_f32 v[152:153], v[152:153], v[184:185], v[128:129] op_sel_hi:[1,0,1]
	v_add_f32_e32 v160, 1.0, v183
	v_pk_fma_f32 v[130:131], v[130:131], v[184:185], v[114:115] op_sel_hi:[1,0,1]
	v_add_f32_e32 v161, 1.0, v161
	v_mul_f32_e32 v183, 0xbfb8aa3b, v152
	v_mul_f32_e32 v185, 0xbfb8aa3b, v153
	v_rcp_f32_e32 v160, v160
	v_rcp_f32_e32 v161, v161
	v_exp_f32_e32 v183, v183
	v_exp_f32_e32 v185, v185
	s_lshl_b32 s3, s30, 8
	v_pk_mul_f32 v[150:151], v[150:151], v[160:161]
	v_add_f32_e32 v160, 1.0, v183
	v_add_f32_e32 v161, 1.0, v185
	v_rcp_f32_e32 v160, v160
	v_rcp_f32_e32 v161, v161
	v_pk_mul_f32 v[150:151], v[130:131], v[150:151]
	v_pk_fma_f32 v[130:131], v[112:113], v[182:183], v[132:133] op_sel_hi:[1,0,1] neg_lo:[1,0,0] neg_hi:[1,0,0]
	s_add_i32 s3, s3, s45
	v_pk_fma_f32 v[130:131], v[130:131], v[184:185], v[116:117] op_sel_hi:[1,0,1]
	v_pk_mul_f32 v[132:133], v[152:153], v[160:161]
	ds_bpermute_b32 v160, v181, v179 offset:64
	v_pk_mul_f32 v[152:153], v[130:131], v[132:133]
	v_cvt_pk_bf16_f32 v130, v154, v155
	ds_bpermute_b32 v154, v181, v176 offset:64
	v_cvt_pk_bf16_f32 v132, v150, v151
	v_cvt_pk_bf16_f32 v133, v152, v153
	v_add_u32_e32 v180, s3, v180
	v_cvt_pk_bf16_f32 v131, v156, v157
	s_waitcnt lgkmcnt(0)
	v_pk_fma_f32 v[118:119], v[142:143], v[154:155], v[118:119] op_sel_hi:[1,0,1] neg_lo:[1,0,0] neg_hi:[1,0,0]
	v_pk_fma_f32 v[106:107], v[138:139], v[154:155], v[106:107] op_sel_hi:[1,0,1] neg_lo:[1,0,0] neg_hi:[1,0,0]
	v_pk_fma_f32 v[118:119], v[118:119], v[160:161], v[146:147] op_sel_hi:[1,0,1]
	v_pk_fma_f32 v[120:121], v[144:145], v[154:155], v[120:121] op_sel_hi:[1,0,1] neg_lo:[1,0,0] neg_hi:[1,0,0]
	v_mul_f32_e32 v150, 0xbfb8aa3b, v118
	v_exp_f32_e32 v152, v150
	v_mul_f32_e32 v150, 0xbfb8aa3b, v119
	v_exp_f32_e32 v153, v150
	v_mad_i64_i32 v[150:151], s[38:39], v180, s65, v[158:159]
	v_add_f32_e32 v152, 1.0, v152
	v_add_f32_e32 v153, 1.0, v153
	v_rcp_f32_e32 v152, v152
	v_rcp_f32_e32 v153, v153
	v_pk_fma_f32 v[106:107], v[106:107], v[160:161], v[134:135] op_sel_hi:[1,0,1]
	v_pk_fma_f32 v[120:121], v[120:121], v[160:161], v[148:149] op_sel_hi:[1,0,1]
	global_store_dwordx4 v[150:151], v[130:133], off sc1
	v_pk_mul_f32 v[118:119], v[118:119], v[152:153]
	v_pk_fma_f32 v[108:109], v[140:141], v[154:155], v[108:109] op_sel_hi:[1,0,1] neg_lo:[1,0,0] neg_hi:[1,0,0]
	v_mul_f32_e32 v130, 0xbfb8aa3b, v120
	v_pk_mul_f32 v[106:107], v[106:107], v[118:119]
	v_mul_f32_e32 v118, 0xbfb8aa3b, v121
	v_exp_f32_e32 v130, v130
	v_exp_f32_e32 v119, v118
	v_pk_fma_f32 v[102:103], v[122:123], v[154:155], v[102:103] op_sel_hi:[1,0,1] neg_lo:[1,0,0] neg_hi:[1,0,0]
	v_pk_fma_f32 v[108:109], v[108:109], v[160:161], v[136:137] op_sel_hi:[1,0,1]
	v_add_f32_e32 v118, 1.0, v130
	v_add_f32_e32 v119, 1.0, v119
	v_rcp_f32_e32 v118, v118
	v_rcp_f32_e32 v119, v119
	v_pk_fma_f32 v[102:103], v[102:103], v[160:161], v[126:127] op_sel_hi:[1,0,1]
	v_pk_fma_f32 v[104:105], v[124:125], v[154:155], v[104:105] op_sel_hi:[1,0,1] neg_lo:[1,0,0] neg_hi:[1,0,0]
	v_mul_f32_e32 v130, 0xbfb8aa3b, v102
	v_pk_mul_f32 v[118:119], v[120:121], v[118:119]
	v_exp_f32_e32 v130, v130
	v_pk_mul_f32 v[108:109], v[108:109], v[118:119]
	v_mul_f32_e32 v119, 0xbfb8aa3b, v103
	v_exp_f32_e32 v119, v119
	v_pk_fma_f32 v[104:105], v[104:105], v[160:161], v[128:129] op_sel_hi:[1,0,1]
	v_add_f32_e32 v118, 1.0, v130
	v_mul_f32_e32 v120, 0xbfb8aa3b, v104
	v_add_f32_e32 v119, 1.0, v119
	v_mul_f32_e32 v121, 0xbfb8aa3b, v105
	v_rcp_f32_e32 v118, v118
	v_rcp_f32_e32 v119, v119
	v_exp_f32_e32 v120, v120
	v_exp_f32_e32 v121, v121
	v_pk_fma_f32 v[98:99], v[110:111], v[154:155], v[98:99] op_sel_hi:[1,0,1] neg_lo:[1,0,0] neg_hi:[1,0,0]
	v_pk_mul_f32 v[102:103], v[102:103], v[118:119]
	v_add_f32_e32 v118, 1.0, v120
	v_add_f32_e32 v119, 1.0, v121
	v_rcp_f32_e32 v118, v118
	v_rcp_f32_e32 v119, v119
	v_pk_fma_f32 v[98:99], v[98:99], v[160:161], v[114:115] op_sel_hi:[1,0,1]
	s_andn2_b64 vcc, exec, s[0:1]
	v_pk_mul_f32 v[102:103], v[98:99], v[102:103]
	v_pk_fma_f32 v[98:99], v[112:113], v[154:155], v[100:101] op_sel_hi:[1,0,1] neg_lo:[1,0,0] neg_hi:[1,0,0]
	v_pk_mul_f32 v[100:101], v[104:105], v[118:119]
	v_pk_fma_f32 v[98:99], v[98:99], v[160:161], v[116:117] op_sel_hi:[1,0,1]
	ds_bpermute_b32 v118, v181, v179 offset:128
	v_pk_mul_f32 v[104:105], v[98:99], v[100:101]
	v_cvt_pk_bf16_f32 v98, v106, v107
	ds_bpermute_b32 v106, v181, v176 offset:128
	v_add_u32_e32 v119, 16, v180
	v_cvt_pk_bf16_f32 v100, v102, v103
	v_cvt_pk_bf16_f32 v101, v104, v105
	v_cvt_pk_bf16_f32 v99, v108, v109
	s_waitcnt lgkmcnt(0)
	v_pk_fma_f32 v[94:95], v[142:143], v[106:107], v[94:95] op_sel_hi:[1,0,1] neg_lo:[1,0,0] neg_hi:[1,0,0]
	v_pk_fma_f32 v[90:91], v[138:139], v[106:107], v[90:91] op_sel_hi:[1,0,1] neg_lo:[1,0,0] neg_hi:[1,0,0]
	v_pk_fma_f32 v[94:95], v[94:95], v[118:119], v[146:147] op_sel_hi:[1,0,1]
	v_pk_fma_f32 v[96:97], v[144:145], v[106:107], v[96:97] op_sel_hi:[1,0,1] neg_lo:[1,0,0] neg_hi:[1,0,0]
	v_mul_f32_e32 v102, 0xbfb8aa3b, v94
	v_exp_f32_e32 v104, v102
	v_mul_f32_e32 v102, 0xbfb8aa3b, v95
	v_exp_f32_e32 v105, v102
	v_mad_i64_i32 v[102:103], s[38:39], v119, s65, v[158:159]
	v_add_f32_e32 v104, 1.0, v104
	v_add_f32_e32 v105, 1.0, v105
	v_rcp_f32_e32 v104, v104
	v_rcp_f32_e32 v105, v105
	v_pk_fma_f32 v[90:91], v[90:91], v[118:119], v[134:135] op_sel_hi:[1,0,1]
	v_pk_fma_f32 v[96:97], v[96:97], v[118:119], v[148:149] op_sel_hi:[1,0,1]
	global_store_dwordx4 v[102:103], v[98:101], off sc1
	v_pk_mul_f32 v[94:95], v[94:95], v[104:105]
	v_pk_fma_f32 v[92:93], v[140:141], v[106:107], v[92:93] op_sel_hi:[1,0,1] neg_lo:[1,0,0] neg_hi:[1,0,0]
	v_mul_f32_e32 v98, 0xbfb8aa3b, v96
	v_pk_mul_f32 v[90:91], v[90:91], v[94:95]
	v_mul_f32_e32 v94, 0xbfb8aa3b, v97
	v_exp_f32_e32 v98, v98
	v_exp_f32_e32 v95, v94
	v_pk_fma_f32 v[86:87], v[122:123], v[106:107], v[86:87] op_sel_hi:[1,0,1] neg_lo:[1,0,0] neg_hi:[1,0,0]
	v_pk_fma_f32 v[92:93], v[92:93], v[118:119], v[136:137] op_sel_hi:[1,0,1]
	v_add_f32_e32 v94, 1.0, v98
	v_add_f32_e32 v95, 1.0, v95
	v_rcp_f32_e32 v94, v94
	v_rcp_f32_e32 v95, v95
	v_pk_fma_f32 v[86:87], v[86:87], v[118:119], v[126:127] op_sel_hi:[1,0,1]
	v_pk_fma_f32 v[88:89], v[124:125], v[106:107], v[88:89] op_sel_hi:[1,0,1] neg_lo:[1,0,0] neg_hi:[1,0,0]
	v_mul_f32_e32 v98, 0xbfb8aa3b, v86
	v_pk_mul_f32 v[94:95], v[96:97], v[94:95]
	v_exp_f32_e32 v98, v98
	v_pk_mul_f32 v[92:93], v[92:93], v[94:95]
	v_mul_f32_e32 v95, 0xbfb8aa3b, v87
	v_exp_f32_e32 v95, v95
	v_pk_fma_f32 v[88:89], v[88:89], v[118:119], v[128:129] op_sel_hi:[1,0,1]
	v_add_f32_e32 v94, 1.0, v98
	v_mul_f32_e32 v96, 0xbfb8aa3b, v88
	v_add_f32_e32 v95, 1.0, v95
	v_mul_f32_e32 v97, 0xbfb8aa3b, v89
	v_rcp_f32_e32 v94, v94
	v_rcp_f32_e32 v95, v95
	v_exp_f32_e32 v96, v96
	v_exp_f32_e32 v97, v97
	v_pk_fma_f32 v[82:83], v[110:111], v[106:107], v[82:83] op_sel_hi:[1,0,1] neg_lo:[1,0,0] neg_hi:[1,0,0]
	v_pk_mul_f32 v[86:87], v[86:87], v[94:95]
	v_add_f32_e32 v94, 1.0, v96
	v_add_f32_e32 v95, 1.0, v97
	v_rcp_f32_e32 v94, v94
	v_rcp_f32_e32 v95, v95
	v_pk_fma_f32 v[82:83], v[82:83], v[118:119], v[114:115] op_sel_hi:[1,0,1]
	s_mov_b64 s[0:1], -1
	v_pk_mul_f32 v[86:87], v[82:83], v[86:87]
	v_pk_fma_f32 v[82:83], v[112:113], v[106:107], v[84:85] op_sel_hi:[1,0,1] neg_lo:[1,0,0] neg_hi:[1,0,0]
	v_pk_mul_f32 v[84:85], v[88:89], v[94:95]
	v_pk_fma_f32 v[82:83], v[82:83], v[118:119], v[116:117] op_sel_hi:[1,0,1]
	ds_bpermute_b32 v94, v181, v179 offset:192
	v_pk_mul_f32 v[88:89], v[82:83], v[84:85]
	v_cvt_pk_bf16_f32 v82, v90, v91
	ds_bpermute_b32 v90, v181, v176 offset:192
	v_add_u32_e32 v95, 32, v180
	v_cvt_pk_bf16_f32 v84, v86, v87
	v_cvt_pk_bf16_f32 v85, v88, v89
	v_cvt_pk_bf16_f32 v83, v92, v93
	s_waitcnt lgkmcnt(0)
	v_pk_fma_f32 v[78:79], v[142:143], v[90:91], v[78:79] op_sel_hi:[1,0,1] neg_lo:[1,0,0] neg_hi:[1,0,0]
	v_pk_fma_f32 v[74:75], v[138:139], v[90:91], v[74:75] op_sel_hi:[1,0,1] neg_lo:[1,0,0] neg_hi:[1,0,0]
	v_pk_fma_f32 v[78:79], v[78:79], v[94:95], v[146:147] op_sel_hi:[1,0,1]
	v_pk_fma_f32 v[80:81], v[144:145], v[90:91], v[80:81] op_sel_hi:[1,0,1] neg_lo:[1,0,0] neg_hi:[1,0,0]
	v_mul_f32_e32 v86, 0xbfb8aa3b, v78
	v_exp_f32_e32 v88, v86
	v_mul_f32_e32 v86, 0xbfb8aa3b, v79
	v_exp_f32_e32 v89, v86
	v_mad_i64_i32 v[86:87], s[38:39], v95, s65, v[158:159]
	v_add_f32_e32 v88, 1.0, v88
	v_add_f32_e32 v89, 1.0, v89
	v_rcp_f32_e32 v88, v88
	v_rcp_f32_e32 v89, v89
	v_pk_fma_f32 v[74:75], v[74:75], v[94:95], v[134:135] op_sel_hi:[1,0,1]
	v_pk_fma_f32 v[80:81], v[80:81], v[94:95], v[148:149] op_sel_hi:[1,0,1]
	global_store_dwordx4 v[86:87], v[82:85], off sc1
	v_pk_mul_f32 v[78:79], v[78:79], v[88:89]
	v_pk_fma_f32 v[76:77], v[140:141], v[90:91], v[76:77] op_sel_hi:[1,0,1] neg_lo:[1,0,0] neg_hi:[1,0,0]
	v_mul_f32_e32 v82, 0xbfb8aa3b, v80
	v_pk_mul_f32 v[74:75], v[74:75], v[78:79]
	v_mul_f32_e32 v78, 0xbfb8aa3b, v81
	v_exp_f32_e32 v82, v82
	v_exp_f32_e32 v79, v78
	v_pk_fma_f32 v[70:71], v[122:123], v[90:91], v[70:71] op_sel_hi:[1,0,1] neg_lo:[1,0,0] neg_hi:[1,0,0]
	v_pk_fma_f32 v[76:77], v[76:77], v[94:95], v[136:137] op_sel_hi:[1,0,1]
	v_add_f32_e32 v78, 1.0, v82
	v_add_f32_e32 v79, 1.0, v79
	v_rcp_f32_e32 v78, v78
	v_rcp_f32_e32 v79, v79
	v_pk_fma_f32 v[70:71], v[70:71], v[94:95], v[126:127] op_sel_hi:[1,0,1]
	v_pk_fma_f32 v[72:73], v[124:125], v[90:91], v[72:73] op_sel_hi:[1,0,1] neg_lo:[1,0,0] neg_hi:[1,0,0]
	v_mul_f32_e32 v82, 0xbfb8aa3b, v70
	v_pk_mul_f32 v[78:79], v[80:81], v[78:79]
	v_exp_f32_e32 v82, v82
	v_pk_mul_f32 v[76:77], v[76:77], v[78:79]
	v_mul_f32_e32 v79, 0xbfb8aa3b, v71
	v_exp_f32_e32 v79, v79
	v_pk_fma_f32 v[72:73], v[72:73], v[94:95], v[128:129] op_sel_hi:[1,0,1]
	v_add_f32_e32 v78, 1.0, v82
	v_mul_f32_e32 v80, 0xbfb8aa3b, v72
	v_add_f32_e32 v79, 1.0, v79
	v_mul_f32_e32 v81, 0xbfb8aa3b, v73
	v_rcp_f32_e32 v78, v78
	v_rcp_f32_e32 v79, v79
	v_exp_f32_e32 v80, v80
	v_exp_f32_e32 v81, v81
	v_pk_fma_f32 v[66:67], v[110:111], v[90:91], v[66:67] op_sel_hi:[1,0,1] neg_lo:[1,0,0] neg_hi:[1,0,0]
	v_pk_mul_f32 v[70:71], v[70:71], v[78:79]
	v_add_f32_e32 v78, 1.0, v80
	v_add_f32_e32 v79, 1.0, v81
	v_rcp_f32_e32 v78, v78
	v_rcp_f32_e32 v79, v79
	v_pk_fma_f32 v[66:67], v[66:67], v[94:95], v[114:115] op_sel_hi:[1,0,1]
	s_nop 0
	v_pk_mul_f32 v[70:71], v[66:67], v[70:71]
	v_pk_fma_f32 v[66:67], v[112:113], v[90:91], v[68:69] op_sel_hi:[1,0,1] neg_lo:[1,0,0] neg_hi:[1,0,0]
	v_pk_mul_f32 v[68:69], v[72:73], v[78:79]
	v_pk_fma_f32 v[66:67], v[66:67], v[94:95], v[116:117] op_sel_hi:[1,0,1]
	v_add_u32_e32 v78, 48, v180
	v_pk_mul_f32 v[72:73], v[66:67], v[68:69]
	v_cvt_pk_bf16_f32 v68, v70, v71
	ds_bpermute_b32 v70, v181, v174
	v_cvt_pk_bf16_f32 v66, v74, v75
	ds_bpermute_b32 v74, v181, v175
	v_cvt_pk_bf16_f32 v67, v76, v77
	v_cvt_pk_bf16_f32 v69, v72, v73
	s_waitcnt lgkmcnt(0)
	v_pk_fma_f32 v[62:63], v[142:143], v[70:71], v[62:63] op_sel_hi:[1,0,1] neg_lo:[1,0,0] neg_hi:[1,0,0]
	v_mad_i64_i32 v[72:73], s[38:39], v78, s65, v[158:159]
	v_pk_fma_f32 v[62:63], v[62:63], v[74:75], v[146:147] op_sel_hi:[1,0,1]
	global_store_dwordx4 v[72:73], v[66:69], off sc1
	s_cbranch_vccnz .Lup_stats_skip
	s_lshl_b32 s0, s22, 8
	s_add_i32 s0, s0, s45
	v_add_u32_e32 v232, s0, v177
	v_ashrrev_i32_e32 v233, 31, v232
	v_lshlrev_b64 v[228:229], 7, v[232:233]
	v_add_u32_e32 v232, 0x80, v232
	v_ashrrev_i32_e32 v233, 31, v232
	v_lshlrev_b64 v[230:231], 7, v[232:233]
	v_lshl_add_u64 v[228:229], s[94:95], 0, v[228:229]
	v_lshl_add_u64 v[230:231], s[94:95], 0, v[230:231]
	global_load_dwordx4 v[224:227], v[228:229], off
	global_load_dwordx4 v[216:219], v[228:229], off offset:16
	global_load_dwordx4 v[212:215], v[228:229], off offset:32
	global_load_dwordx4 v[208:211], v[228:229], off offset:48
	global_load_dwordx4 v[204:207], v[228:229], off offset:64
	global_load_dwordx4 v[200:203], v[228:229], off offset:80
	global_load_dwordx4 v[196:199], v[228:229], off offset:96
	global_load_dwordx4 v[154:157], v[228:229], off offset:112
	global_load_dwordx4 v[150:153], v[230:231], off
	global_load_dwordx4 v[130:133], v[230:231], off offset:16
	global_load_dwordx4 v[118:121], v[230:231], off offset:32
	global_load_dwordx4 v[104:107], v[230:231], off offset:48
	global_load_dwordx4 v[100:103], v[230:231], off offset:64
	global_load_dwordx4 v[96:99], v[230:231], off offset:80
	global_load_dwordx4 v[92:95], v[230:231], off offset:96
	global_load_dwordx4 v[88:91], v[230:231], off offset:112
.Lup_stats_skip:
	v_mul_f32_e32 v71, 0xbfb8aa3b, v62
	v_mul_f32_e32 v75, 0xbfb8aa3b, v63
	v_exp_f32_e32 v71, v71
	v_exp_f32_e32 v75, v75
	v_add_u32_e32 v68, 0x80, v180
	v_add_f32_e32 v66, 1.0, v71
	v_add_f32_e32 v67, 1.0, v75
	v_rcp_f32_e32 v66, v66
	v_rcp_f32_e32 v67, v67
	v_pk_fma_f32 v[58:59], v[138:139], v[70:71], v[58:59] op_sel_hi:[1,0,1] neg_lo:[1,0,0] neg_hi:[1,0,0]
	v_pk_fma_f32 v[64:65], v[144:145], v[70:71], v[64:65] op_sel_hi:[1,0,1] neg_lo:[1,0,0] neg_hi:[1,0,0]
	v_pk_fma_f32 v[58:59], v[58:59], v[74:75], v[134:135] op_sel_hi:[1,0,1]
	v_pk_mul_f32 v[62:63], v[62:63], v[66:67]
	v_pk_fma_f32 v[64:65], v[64:65], v[74:75], v[148:149] op_sel_hi:[1,0,1]
	v_pk_mul_f32 v[58:59], v[58:59], v[62:63]
	v_mul_f32_e32 v66, 0xbfb8aa3b, v64
	v_mul_f32_e32 v62, 0xbfb8aa3b, v65
	v_exp_f32_e32 v66, v66
	v_exp_f32_e32 v63, v62
	v_pk_fma_f32 v[60:61], v[140:141], v[70:71], v[60:61] op_sel_hi:[1,0,1] neg_lo:[1,0,0] neg_hi:[1,0,0]
	v_pk_fma_f32 v[54:55], v[122:123], v[70:71], v[54:55] op_sel_hi:[1,0,1] neg_lo:[1,0,0] neg_hi:[1,0,0]
	v_add_f32_e32 v62, 1.0, v66
	v_add_f32_e32 v63, 1.0, v63
	v_rcp_f32_e32 v62, v62
	v_rcp_f32_e32 v63, v63
	v_pk_fma_f32 v[54:55], v[54:55], v[74:75], v[126:127] op_sel_hi:[1,0,1]
	v_pk_fma_f32 v[60:61], v[60:61], v[74:75], v[136:137] op_sel_hi:[1,0,1]
	v_mul_f32_e32 v66, 0xbfb8aa3b, v54
	v_pk_mul_f32 v[62:63], v[64:65], v[62:63]
	v_exp_f32_e32 v66, v66
	v_pk_mul_f32 v[60:61], v[60:61], v[62:63]
	v_mul_f32_e32 v63, 0xbfb8aa3b, v55
	v_exp_f32_e32 v63, v63
	v_pk_fma_f32 v[56:57], v[124:125], v[70:71], v[56:57] op_sel_hi:[1,0,1] neg_lo:[1,0,0] neg_hi:[1,0,0]
	v_add_f32_e32 v62, 1.0, v66
	v_pk_fma_f32 v[56:57], v[56:57], v[74:75], v[128:129] op_sel_hi:[1,0,1]
	v_add_f32_e32 v63, 1.0, v63
	v_mul_f32_e32 v64, 0xbfb8aa3b, v56
	v_mul_f32_e32 v65, 0xbfb8aa3b, v57
	v_rcp_f32_e32 v62, v62
	v_rcp_f32_e32 v63, v63
	v_exp_f32_e32 v64, v64
	v_exp_f32_e32 v65, v65
	v_pk_fma_f32 v[50:51], v[110:111], v[70:71], v[50:51] op_sel_hi:[1,0,1] neg_lo:[1,0,0] neg_hi:[1,0,0]
	v_pk_mul_f32 v[54:55], v[54:55], v[62:63]
	v_add_f32_e32 v62, 1.0, v64
	v_add_f32_e32 v63, 1.0, v65
	v_rcp_f32_e32 v62, v62
	v_rcp_f32_e32 v63, v63
	v_pk_fma_f32 v[50:51], v[50:51], v[74:75], v[114:115] op_sel_hi:[1,0,1]
	s_nop 0
	v_pk_mul_f32 v[54:55], v[50:51], v[54:55]
	v_pk_fma_f32 v[50:51], v[112:113], v[70:71], v[52:53] op_sel_hi:[1,0,1] neg_lo:[1,0,0] neg_hi:[1,0,0]
	v_pk_mul_f32 v[52:53], v[56:57], v[62:63]
	v_pk_fma_f32 v[50:51], v[50:51], v[74:75], v[116:117] op_sel_hi:[1,0,1]
	ds_bpermute_b32 v62, v181, v175 offset:64
	v_pk_mul_f32 v[56:57], v[50:51], v[52:53]
	v_cvt_pk_bf16_f32 v50, v58, v59
	ds_bpermute_b32 v58, v181, v174 offset:64
	v_cvt_pk_bf16_f32 v52, v54, v55
	v_cvt_pk_bf16_f32 v53, v56, v57
	v_cvt_pk_bf16_f32 v51, v60, v61
	s_waitcnt lgkmcnt(0)
	v_pk_fma_f32 v[46:47], v[142:143], v[58:59], v[46:47] op_sel_hi:[1,0,1] neg_lo:[1,0,0] neg_hi:[1,0,0]
	s_nop 0
	v_pk_fma_f32 v[46:47], v[46:47], v[62:63], v[146:147] op_sel_hi:[1,0,1]
	v_pk_fma_f32 v[42:43], v[138:139], v[58:59], v[42:43] op_sel_hi:[1,0,1] neg_lo:[1,0,0] neg_hi:[1,0,0]
	v_mul_f32_e32 v54, 0xbfb8aa3b, v46
	v_exp_f32_e32 v56, v54
	v_mul_f32_e32 v54, 0xbfb8aa3b, v47
	v_exp_f32_e32 v57, v54
	v_pk_fma_f32 v[48:49], v[144:145], v[58:59], v[48:49] op_sel_hi:[1,0,1] neg_lo:[1,0,0] neg_hi:[1,0,0]
	v_add_f32_e32 v56, 1.0, v56
	v_rcp_f32_e32 v56, v56
	v_add_f32_e32 v57, 1.0, v57
	v_rcp_f32_e32 v57, v57
	v_mad_i64_i32 v[54:55], s[38:39], v68, s65, v[158:159]
	v_pk_fma_f32 v[42:43], v[42:43], v[62:63], v[134:135] op_sel_hi:[1,0,1]
	v_pk_mul_f32 v[46:47], v[46:47], v[56:57]
	v_pk_fma_f32 v[48:49], v[48:49], v[62:63], v[148:149] op_sel_hi:[1,0,1]
	global_store_dwordx4 v[54:55], v[50:53], off sc1
	v_pk_mul_f32 v[42:43], v[42:43], v[46:47]
	v_mul_f32_e32 v46, 0xbfb8aa3b, v49
	v_mul_f32_e32 v50, 0xbfb8aa3b, v48
	v_exp_f32_e32 v50, v50
	v_exp_f32_e32 v47, v46
	v_pk_fma_f32 v[44:45], v[140:141], v[58:59], v[44:45] op_sel_hi:[1,0,1] neg_lo:[1,0,0] neg_hi:[1,0,0]
	v_pk_fma_f32 v[38:39], v[122:123], v[58:59], v[38:39] op_sel_hi:[1,0,1] neg_lo:[1,0,0] neg_hi:[1,0,0]
	v_add_f32_e32 v46, 1.0, v50
	v_add_f32_e32 v47, 1.0, v47
	v_rcp_f32_e32 v46, v46
	v_rcp_f32_e32 v47, v47
	v_pk_fma_f32 v[38:39], v[38:39], v[62:63], v[126:127] op_sel_hi:[1,0,1]
	v_pk_fma_f32 v[44:45], v[44:45], v[62:63], v[136:137] op_sel_hi:[1,0,1]
	v_mul_f32_e32 v50, 0xbfb8aa3b, v38
	v_pk_mul_f32 v[46:47], v[48:49], v[46:47]
	v_exp_f32_e32 v50, v50
	v_pk_mul_f32 v[44:45], v[44:45], v[46:47]
	v_mul_f32_e32 v47, 0xbfb8aa3b, v39
	v_exp_f32_e32 v47, v47
	v_pk_fma_f32 v[40:41], v[124:125], v[58:59], v[40:41] op_sel_hi:[1,0,1] neg_lo:[1,0,0] neg_hi:[1,0,0]
	v_add_f32_e32 v46, 1.0, v50
	v_pk_fma_f32 v[40:41], v[40:41], v[62:63], v[128:129] op_sel_hi:[1,0,1]
	v_add_f32_e32 v47, 1.0, v47
	v_mul_f32_e32 v48, 0xbfb8aa3b, v40
	v_mul_f32_e32 v49, 0xbfb8aa3b, v41
	v_rcp_f32_e32 v46, v46
	v_rcp_f32_e32 v47, v47
	v_exp_f32_e32 v48, v48
	v_exp_f32_e32 v49, v49
	v_pk_fma_f32 v[34:35], v[110:111], v[58:59], v[34:35] op_sel_hi:[1,0,1] neg_lo:[1,0,0] neg_hi:[1,0,0]
	v_pk_mul_f32 v[38:39], v[38:39], v[46:47]
	v_add_f32_e32 v46, 1.0, v48
	v_add_f32_e32 v47, 1.0, v49
	v_rcp_f32_e32 v46, v46
	v_rcp_f32_e32 v47, v47
	v_pk_fma_f32 v[34:35], v[34:35], v[62:63], v[114:115] op_sel_hi:[1,0,1]
	s_nop 0
	v_pk_mul_f32 v[38:39], v[34:35], v[38:39]
	v_pk_fma_f32 v[34:35], v[112:113], v[58:59], v[36:37] op_sel_hi:[1,0,1] neg_lo:[1,0,0] neg_hi:[1,0,0]
	v_pk_mul_f32 v[36:37], v[40:41], v[46:47]
	v_pk_fma_f32 v[34:35], v[34:35], v[62:63], v[116:117] op_sel_hi:[1,0,1]
	ds_bpermute_b32 v46, v181, v175 offset:128
	v_pk_mul_f32 v[40:41], v[34:35], v[36:37]
	v_cvt_pk_bf16_f32 v34, v42, v43
	ds_bpermute_b32 v42, v181, v174 offset:128
	v_add_u32_e32 v47, 0x90, v180
	v_cvt_pk_bf16_f32 v36, v38, v39
	v_cvt_pk_bf16_f32 v37, v40, v41
	v_cvt_pk_bf16_f32 v35, v44, v45
	s_waitcnt lgkmcnt(0)
	v_pk_fma_f32 v[30:31], v[142:143], v[42:43], v[30:31] op_sel_hi:[1,0,1] neg_lo:[1,0,0] neg_hi:[1,0,0]
	v_pk_fma_f32 v[26:27], v[138:139], v[42:43], v[26:27] op_sel_hi:[1,0,1] neg_lo:[1,0,0] neg_hi:[1,0,0]
	v_pk_fma_f32 v[30:31], v[30:31], v[46:47], v[146:147] op_sel_hi:[1,0,1]
	v_pk_fma_f32 v[32:33], v[144:145], v[42:43], v[32:33] op_sel_hi:[1,0,1] neg_lo:[1,0,0] neg_hi:[1,0,0]
	v_mul_f32_e32 v38, 0xbfb8aa3b, v30
	v_exp_f32_e32 v40, v38
	v_mul_f32_e32 v38, 0xbfb8aa3b, v31
	v_exp_f32_e32 v41, v38
	v_mad_i64_i32 v[38:39], s[38:39], v47, s65, v[158:159]
	v_add_f32_e32 v40, 1.0, v40
	v_add_f32_e32 v41, 1.0, v41
	v_rcp_f32_e32 v40, v40
	v_rcp_f32_e32 v41, v41
	v_pk_fma_f32 v[26:27], v[26:27], v[46:47], v[134:135] op_sel_hi:[1,0,1]
	v_pk_fma_f32 v[32:33], v[32:33], v[46:47], v[148:149] op_sel_hi:[1,0,1]
	global_store_dwordx4 v[38:39], v[34:37], off sc1
	v_pk_mul_f32 v[30:31], v[30:31], v[40:41]
	v_pk_fma_f32 v[28:29], v[140:141], v[42:43], v[28:29] op_sel_hi:[1,0,1] neg_lo:[1,0,0] neg_hi:[1,0,0]
	v_mul_f32_e32 v34, 0xbfb8aa3b, v32
	v_pk_mul_f32 v[26:27], v[26:27], v[30:31]
	v_mul_f32_e32 v30, 0xbfb8aa3b, v33
	v_exp_f32_e32 v34, v34
	v_exp_f32_e32 v31, v30
	v_pk_fma_f32 v[22:23], v[122:123], v[42:43], v[22:23] op_sel_hi:[1,0,1] neg_lo:[1,0,0] neg_hi:[1,0,0]
	v_pk_fma_f32 v[28:29], v[28:29], v[46:47], v[136:137] op_sel_hi:[1,0,1]
	v_add_f32_e32 v30, 1.0, v34
	v_add_f32_e32 v31, 1.0, v31
	v_rcp_f32_e32 v30, v30
	v_rcp_f32_e32 v31, v31
	v_pk_fma_f32 v[22:23], v[22:23], v[46:47], v[126:127] op_sel_hi:[1,0,1]
	v_pk_fma_f32 v[24:25], v[124:125], v[42:43], v[24:25] op_sel_hi:[1,0,1] neg_lo:[1,0,0] neg_hi:[1,0,0]
	v_mul_f32_e32 v34, 0xbfb8aa3b, v22
	v_pk_mul_f32 v[30:31], v[32:33], v[30:31]
	v_exp_f32_e32 v34, v34
	v_pk_mul_f32 v[28:29], v[28:29], v[30:31]
	v_mul_f32_e32 v31, 0xbfb8aa3b, v23
	v_exp_f32_e32 v31, v31
	v_pk_fma_f32 v[24:25], v[24:25], v[46:47], v[128:129] op_sel_hi:[1,0,1]
	v_add_f32_e32 v30, 1.0, v34
	v_mul_f32_e32 v32, 0xbfb8aa3b, v24
	v_add_f32_e32 v31, 1.0, v31
	v_mul_f32_e32 v33, 0xbfb8aa3b, v25
	v_rcp_f32_e32 v30, v30
	v_rcp_f32_e32 v31, v31
	v_exp_f32_e32 v32, v32
	v_exp_f32_e32 v33, v33
	v_pk_fma_f32 v[18:19], v[110:111], v[42:43], v[18:19] op_sel_hi:[1,0,1] neg_lo:[1,0,0] neg_hi:[1,0,0]
	v_pk_mul_f32 v[22:23], v[22:23], v[30:31]
	v_add_f32_e32 v30, 1.0, v32
	v_add_f32_e32 v31, 1.0, v33
	v_rcp_f32_e32 v30, v30
	v_rcp_f32_e32 v31, v31
	v_pk_fma_f32 v[18:19], v[18:19], v[46:47], v[114:115] op_sel_hi:[1,0,1]
	s_nop 0
	v_pk_mul_f32 v[22:23], v[18:19], v[22:23]
	v_pk_fma_f32 v[18:19], v[112:113], v[42:43], v[20:21] op_sel_hi:[1,0,1] neg_lo:[1,0,0] neg_hi:[1,0,0]
	v_pk_mul_f32 v[20:21], v[24:25], v[30:31]
	v_pk_fma_f32 v[18:19], v[18:19], v[46:47], v[116:117] op_sel_hi:[1,0,1]
	ds_bpermute_b32 v30, v181, v175 offset:192
	v_pk_mul_f32 v[24:25], v[18:19], v[20:21]
	v_cvt_pk_bf16_f32 v18, v26, v27
	ds_bpermute_b32 v26, v181, v174 offset:192
	v_add_u32_e32 v31, 0xa0, v180
	v_cvt_pk_bf16_f32 v20, v22, v23
	v_cvt_pk_bf16_f32 v21, v24, v25
	v_cvt_pk_bf16_f32 v19, v28, v29
	s_waitcnt lgkmcnt(0)
	v_pk_fma_f32 v[14:15], v[142:143], v[26:27], v[14:15] op_sel_hi:[1,0,1] neg_lo:[1,0,0] neg_hi:[1,0,0]
	v_pk_fma_f32 v[10:11], v[138:139], v[26:27], v[10:11] op_sel_hi:[1,0,1] neg_lo:[1,0,0] neg_hi:[1,0,0]
	v_pk_fma_f32 v[14:15], v[14:15], v[30:31], v[146:147] op_sel_hi:[1,0,1]
	v_pk_fma_f32 v[16:17], v[144:145], v[26:27], v[16:17] op_sel_hi:[1,0,1] neg_lo:[1,0,0] neg_hi:[1,0,0]
	v_mul_f32_e32 v22, 0xbfb8aa3b, v14
	v_exp_f32_e32 v24, v22
	v_mul_f32_e32 v22, 0xbfb8aa3b, v15
	v_exp_f32_e32 v25, v22
	v_mad_i64_i32 v[22:23], s[38:39], v31, s65, v[158:159]
	v_add_f32_e32 v24, 1.0, v24
	v_add_f32_e32 v25, 1.0, v25
	v_rcp_f32_e32 v24, v24
	v_rcp_f32_e32 v25, v25
	v_pk_fma_f32 v[10:11], v[10:11], v[30:31], v[134:135] op_sel_hi:[1,0,1]
	v_pk_fma_f32 v[16:17], v[16:17], v[30:31], v[148:149] op_sel_hi:[1,0,1]
	global_store_dwordx4 v[22:23], v[18:21], off sc1
	v_pk_mul_f32 v[14:15], v[14:15], v[24:25]
	v_pk_fma_f32 v[12:13], v[140:141], v[26:27], v[12:13] op_sel_hi:[1,0,1] neg_lo:[1,0,0] neg_hi:[1,0,0]
	v_mul_f32_e32 v18, 0xbfb8aa3b, v16
	v_pk_mul_f32 v[10:11], v[10:11], v[14:15]
	v_mul_f32_e32 v14, 0xbfb8aa3b, v17
	v_exp_f32_e32 v18, v18
	v_exp_f32_e32 v15, v14
	v_pk_fma_f32 v[6:7], v[122:123], v[26:27], v[6:7] op_sel_hi:[1,0,1] neg_lo:[1,0,0] neg_hi:[1,0,0]
	v_pk_fma_f32 v[12:13], v[12:13], v[30:31], v[136:137] op_sel_hi:[1,0,1]
	v_add_f32_e32 v14, 1.0, v18
	v_add_f32_e32 v15, 1.0, v15
	v_rcp_f32_e32 v14, v14
	v_rcp_f32_e32 v15, v15
	v_pk_fma_f32 v[6:7], v[6:7], v[30:31], v[126:127] op_sel_hi:[1,0,1]
	v_pk_fma_f32 v[8:9], v[124:125], v[26:27], v[8:9] op_sel_hi:[1,0,1] neg_lo:[1,0,0] neg_hi:[1,0,0]
	v_mul_f32_e32 v18, 0xbfb8aa3b, v6
	v_pk_mul_f32 v[14:15], v[16:17], v[14:15]
	v_exp_f32_e32 v18, v18
	v_pk_mul_f32 v[12:13], v[12:13], v[14:15]
	v_mul_f32_e32 v15, 0xbfb8aa3b, v7
	v_exp_f32_e32 v15, v15
	v_pk_fma_f32 v[8:9], v[8:9], v[30:31], v[128:129] op_sel_hi:[1,0,1]
	v_add_f32_e32 v14, 1.0, v18
	v_mul_f32_e32 v16, 0xbfb8aa3b, v8
	v_add_f32_e32 v15, 1.0, v15
	v_mul_f32_e32 v17, 0xbfb8aa3b, v9
	v_rcp_f32_e32 v14, v14
	v_rcp_f32_e32 v15, v15
	v_exp_f32_e32 v16, v16
	v_exp_f32_e32 v17, v17
	v_pk_fma_f32 v[2:3], v[110:111], v[26:27], v[2:3] op_sel_hi:[1,0,1] neg_lo:[1,0,0] neg_hi:[1,0,0]
	v_pk_mul_f32 v[6:7], v[6:7], v[14:15]
	v_add_f32_e32 v14, 1.0, v16
	v_add_f32_e32 v15, 1.0, v17
	v_rcp_f32_e32 v14, v14
	v_rcp_f32_e32 v15, v15
	v_pk_fma_f32 v[2:3], v[2:3], v[30:31], v[114:115] op_sel_hi:[1,0,1]
	s_nop 0
	v_pk_mul_f32 v[6:7], v[2:3], v[6:7]
	v_pk_fma_f32 v[2:3], v[112:113], v[26:27], v[4:5] op_sel_hi:[1,0,1] neg_lo:[1,0,0] neg_hi:[1,0,0]
	v_pk_mul_f32 v[4:5], v[8:9], v[14:15]
	v_pk_fma_f32 v[2:3], v[2:3], v[30:31], v[116:117] op_sel_hi:[1,0,1]
	v_add_u32_e32 v14, 0xb0, v180
	v_pk_mul_f32 v[8:9], v[2:3], v[4:5]
	v_cvt_pk_bf16_f32 v2, v10, v11
	v_cvt_pk_bf16_f32 v3, v12, v13
	v_cvt_pk_bf16_f32 v4, v6, v7
	v_cvt_pk_bf16_f32 v5, v8, v9
	v_mad_i64_i32 v[6:7], s[38:39], v14, s65, v[158:159]
	global_store_dwordx4 v[6:7], v[2:5], off sc1
	v_writelane_b32 v255, s30, 46
	s_cbranch_vccnz .LBB0_941
	s_andn2_b64 vcc, exec, s[18:19]
	s_cbranch_vccnz .LBB0_940
	s_barrier
	s_branch .LBB0_940
